# v_f1 + leading half starts its SwiGLU epilogue during the trailing half's last MFMA block (ALIGN barrier moved after the 2nd row-group store) in P1/P6
# baseline (speedup 1.0000x reference)
.LBB0_527:
	s_cmp_eq_u32 s24, s33
	s_cselect_b32 s17, 0, 0x400
	v_add_u32_e32 v132, s17, v146
	ds_read2_b32 v[152:153], v132 offset1:16
	ds_read2_b32 v[138:139], v132 offset0:32 offset1:48
	ds_read2_b32 v[136:137], v132 offset0:128 offset1:144
	ds_read2_b32 v[134:135], v132 offset0:160 offset1:176
	v_lshl_add_u32 v133, s24, 8, v144
	v_mov_b64_e32 v[154:155], s[66:67]
	s_waitcnt lgkmcnt(3)
	v_mul_f32_e32 v156, 0xbfb8aa3b, v152
	v_mad_i64_i32 v[154:155], s[26:27], v133, s74, v[154:155]
	v_mul_f32_e32 v133, v152, v152
	v_pk_mul_f32 v[158:159], v[120:121], v[156:157] op_sel_hi:[1,0]
	v_pk_mul_f32 v[160:161], v[122:123], v[156:157] op_sel_hi:[1,0]
	v_rcp_f32_e32 v152, v133
	v_exp_f32_e32 v158, v158
	v_exp_f32_e32 v159, v159
	v_exp_f32_e32 v160, v160
	v_exp_f32_e32 v161, v161
	s_lshl_b32 s17, s82, 7
	v_subrev_u32_e32 v132, s17, v145
	v_ashrrev_i32_e32 v133, 31, v132
	v_lshl_add_u64 v[132:133], v[132:133], 1, v[154:155]
	v_pk_fma_f32 v[154:155], v[152:153], v[158:159], v[152:153] op_sel_hi:[0,1,0]
	v_pk_fma_f32 v[158:159], v[152:153], v[160:161], v[152:153] op_sel_hi:[0,1,0]
	v_rcp_f32_e32 v154, v154
	v_rcp_f32_e32 v155, v155
	v_rcp_f32_e32 v158, v158
	v_rcp_f32_e32 v159, v159
	v_pk_mul_f32 v[120:121], v[120:121], v[124:125]
	v_pk_mul_f32 v[124:125], v[112:113], v[156:157] op_sel_hi:[1,0]
	v_pk_mul_f32 v[122:123], v[122:123], v[126:127]
	v_exp_f32_e32 v124, v124
	v_exp_f32_e32 v125, v125
	v_pk_mul_f32 v[126:127], v[114:115], v[156:157] op_sel_hi:[1,0]
	v_pk_mul_f32 v[120:121], v[120:121], v[154:155]
	v_exp_f32_e32 v126, v126
	v_exp_f32_e32 v127, v127
	v_pk_mul_f32 v[122:123], v[122:123], v[158:159]
	v_cvt_pk_bf16_f32 v120, v120, v121
	v_pk_mul_f32 v[112:113], v[112:113], v[116:117]
	v_cvt_pk_bf16_f32 v121, v122, v123
	v_pk_fma_f32 v[122:123], v[152:153], v[124:125], v[152:153] op_sel_hi:[0,1,0]
	v_rcp_f32_e32 v122, v122
	v_rcp_f32_e32 v123, v123
	v_pk_fma_f32 v[124:125], v[152:153], v[126:127], v[152:153] op_sel_hi:[0,1,0]
	v_rcp_f32_e32 v124, v124
	v_rcp_f32_e32 v125, v125
	v_pk_mul_f32 v[112:113], v[112:113], v[122:123]
	v_pk_mul_f32 v[114:115], v[114:115], v[118:119]
	v_cvt_pk_bf16_f32 v122, v112, v113
	v_mul_f32_e32 v112, 0xbfb8aa3b, v153
	v_mul_f32_e32 v113, v153, v153
	v_pk_mul_f32 v[114:115], v[114:115], v[124:125]
	v_pk_mul_f32 v[118:119], v[104:105], v[112:113] op_sel_hi:[1,0]
	v_pk_mul_f32 v[124:125], v[106:107], v[112:113] op_sel_hi:[1,0]
	v_rcp_f32_e32 v116, v113
	v_exp_f32_e32 v118, v118
	v_exp_f32_e32 v119, v119
	v_exp_f32_e32 v124, v124
	v_exp_f32_e32 v125, v125
	v_cvt_pk_bf16_f32 v123, v114, v115
	v_pk_fma_f32 v[114:115], v[116:117], v[118:119], v[116:117] op_sel_hi:[0,1,0]
	v_rcp_f32_e32 v114, v114
	v_pk_fma_f32 v[118:119], v[116:117], v[124:125], v[116:117] op_sel_hi:[0,1,0]
	v_rcp_f32_e32 v115, v115
	v_rcp_f32_e32 v118, v118
	v_rcp_f32_e32 v119, v119
	v_pk_mul_f32 v[104:105], v[104:105], v[108:109]
	v_pk_mul_f32 v[108:109], v[96:97], v[112:113] op_sel_hi:[1,0]
	v_pk_mul_f32 v[106:107], v[106:107], v[110:111]
	v_exp_f32_e32 v108, v108
	v_exp_f32_e32 v109, v109
	v_pk_mul_f32 v[110:111], v[98:99], v[112:113] op_sel_hi:[1,0]
	v_pk_mul_f32 v[104:105], v[104:105], v[114:115]
	v_exp_f32_e32 v110, v110
	v_exp_f32_e32 v111, v111
	v_pk_mul_f32 v[106:107], v[106:107], v[118:119]
	global_store_dwordx4 v[132:133], v[120:123], off
	v_cvt_pk_bf16_f32 v104, v104, v105
	v_cvt_pk_bf16_f32 v105, v106, v107
	v_pk_fma_f32 v[106:107], v[116:117], v[108:109], v[116:117] op_sel_hi:[0,1,0]
	v_rcp_f32_e32 v106, v106
	v_rcp_f32_e32 v107, v107
	v_pk_fma_f32 v[108:109], v[116:117], v[110:111], v[116:117] op_sel_hi:[0,1,0]
	v_rcp_f32_e32 v108, v108
	v_rcp_f32_e32 v109, v109
	v_pk_mul_f32 v[96:97], v[96:97], v[100:101]
	v_pk_mul_f32 v[98:99], v[98:99], v[102:103]
	v_pk_mul_f32 v[96:97], v[96:97], v[106:107]
	v_pk_mul_f32 v[98:99], v[98:99], v[108:109]
	v_cvt_pk_bf16_f32 v106, v96, v97
	s_waitcnt lgkmcnt(2)
	v_mul_f32_e32 v96, 0xbfb8aa3b, v138
	v_mul_f32_e32 v97, v138, v138
	v_pk_mul_f32 v[100:101], v[88:89], v[96:97] op_sel_hi:[1,0]
	v_pk_mul_f32 v[102:103], v[90:91], v[96:97] op_sel_hi:[1,0]
	v_cvt_pk_bf16_f32 v107, v98, v99
	v_rcp_f32_e32 v98, v97
	v_exp_f32_e32 v100, v100
	v_exp_f32_e32 v101, v101
	v_exp_f32_e32 v102, v102
	v_exp_f32_e32 v103, v103
	v_pk_mul_f32 v[88:89], v[88:89], v[92:93]
	v_pk_fma_f32 v[100:101], v[98:99], v[100:101], v[98:99] op_sel_hi:[0,1,0]
	v_rcp_f32_e32 v100, v100
	v_pk_fma_f32 v[102:103], v[98:99], v[102:103], v[98:99] op_sel_hi:[0,1,0]
	v_rcp_f32_e32 v101, v101
	v_rcp_f32_e32 v102, v102
	v_rcp_f32_e32 v103, v103
	v_pk_mul_f32 v[92:93], v[80:81], v[96:97] op_sel_hi:[1,0]
	v_pk_mul_f32 v[90:91], v[90:91], v[94:95]
	v_exp_f32_e32 v92, v92
	v_exp_f32_e32 v93, v93
	v_pk_mul_f32 v[94:95], v[82:83], v[96:97] op_sel_hi:[1,0]
	v_add_co_u32_e32 v108, vcc, s71, v132
	v_exp_f32_e32 v94, v94
	v_exp_f32_e32 v95, v95
	v_addc_co_u32_e32 v109, vcc, 0, v133, vcc
	v_pk_mul_f32 v[88:89], v[88:89], v[100:101]
	v_pk_mul_f32 v[90:91], v[90:91], v[102:103]
	global_store_dwordx4 v[108:109], v[104:107], off
	s_and_b64 vcc, exec, s[14:15]
	s_cbranch_vccz .Lepibar_p1
	s_barrier
.Lepibar_p1:
	v_cvt_pk_bf16_f32 v88, v88, v89
	v_cvt_pk_bf16_f32 v89, v90, v91
	v_pk_fma_f32 v[90:91], v[98:99], v[92:93], v[98:99] op_sel_hi:[0,1,0]
	v_rcp_f32_e32 v90, v90
	v_rcp_f32_e32 v91, v91
	v_pk_fma_f32 v[92:93], v[98:99], v[94:95], v[98:99] op_sel_hi:[0,1,0]
	v_rcp_f32_e32 v92, v92
	v_rcp_f32_e32 v93, v93
	v_pk_mul_f32 v[80:81], v[80:81], v[84:85]
	v_pk_mul_f32 v[82:83], v[82:83], v[86:87]
	v_pk_mul_f32 v[80:81], v[80:81], v[90:91]
	v_pk_mul_f32 v[82:83], v[82:83], v[92:93]
	v_cvt_pk_bf16_f32 v90, v80, v81
	v_mul_f32_e32 v80, 0xbfb8aa3b, v139
	v_mul_f32_e32 v81, v139, v139
	v_pk_mul_f32 v[84:85], v[72:73], v[80:81] op_sel_hi:[1,0]
	v_pk_mul_f32 v[86:87], v[74:75], v[80:81] op_sel_hi:[1,0]
	v_cvt_pk_bf16_f32 v91, v82, v83
	v_rcp_f32_e32 v82, v81
	v_exp_f32_e32 v84, v84
	v_exp_f32_e32 v85, v85
	v_exp_f32_e32 v86, v86
	v_exp_f32_e32 v87, v87
	v_pk_mul_f32 v[72:73], v[72:73], v[76:77]
	v_pk_fma_f32 v[84:85], v[82:83], v[84:85], v[82:83] op_sel_hi:[0,1,0]
	v_rcp_f32_e32 v84, v84
	v_pk_fma_f32 v[86:87], v[82:83], v[86:87], v[82:83] op_sel_hi:[0,1,0]
	v_rcp_f32_e32 v85, v85
	v_rcp_f32_e32 v86, v86
	v_rcp_f32_e32 v87, v87
	v_pk_mul_f32 v[76:77], v[56:57], v[80:81] op_sel_hi:[1,0]
	v_pk_mul_f32 v[74:75], v[74:75], v[78:79]
	v_exp_f32_e32 v76, v76
	v_exp_f32_e32 v77, v77
	v_pk_mul_f32 v[78:79], v[58:59], v[80:81] op_sel_hi:[1,0]
	v_add_co_u32_e32 v92, vcc, s75, v132
	v_exp_f32_e32 v78, v78
	v_exp_f32_e32 v79, v79
	v_addc_co_u32_e32 v93, vcc, 0, v133, vcc
	v_pk_mul_f32 v[72:73], v[72:73], v[84:85]
	v_pk_mul_f32 v[74:75], v[74:75], v[86:87]
	global_store_dwordx4 v[92:93], v[88:91], off
	v_cvt_pk_bf16_f32 v72, v72, v73
	v_cvt_pk_bf16_f32 v73, v74, v75
	v_pk_fma_f32 v[74:75], v[82:83], v[76:77], v[82:83] op_sel_hi:[0,1,0]
	v_rcp_f32_e32 v74, v74
	v_rcp_f32_e32 v75, v75
	v_pk_fma_f32 v[76:77], v[82:83], v[78:79], v[82:83] op_sel_hi:[0,1,0]
	v_rcp_f32_e32 v76, v76
	v_rcp_f32_e32 v77, v77
	v_pk_mul_f32 v[56:57], v[56:57], v[64:65]
	v_pk_mul_f32 v[58:59], v[58:59], v[66:67]
	v_pk_mul_f32 v[56:57], v[56:57], v[74:75]
	v_pk_mul_f32 v[58:59], v[58:59], v[76:77]
	v_cvt_pk_bf16_f32 v74, v56, v57
	s_waitcnt lgkmcnt(1)
	v_mul_f32_e32 v56, 0xbfb8aa3b, v136
	v_mul_f32_e32 v57, v136, v136
	v_pk_mul_f32 v[64:65], v[60:61], v[56:57] op_sel_hi:[1,0]
	v_cvt_pk_bf16_f32 v75, v58, v59
	v_rcp_f32_e32 v58, v57
	v_exp_f32_e32 v64, v64
	v_exp_f32_e32 v65, v65
	v_pk_mul_f32 v[66:67], v[62:63], v[56:57] op_sel_hi:[1,0]
	v_pk_mul_f32 v[60:61], v[60:61], v[68:69]
	v_exp_f32_e32 v66, v66
	v_exp_f32_e32 v67, v67
	v_pk_fma_f32 v[64:65], v[58:59], v[64:65], v[58:59] op_sel_hi:[0,1,0]
	v_rcp_f32_e32 v64, v64
	v_rcp_f32_e32 v65, v65
	v_pk_fma_f32 v[66:67], v[58:59], v[66:67], v[58:59] op_sel_hi:[0,1,0]
	v_rcp_f32_e32 v66, v66
	v_rcp_f32_e32 v67, v67
	v_pk_mul_f32 v[60:61], v[60:61], v[64:65]
	v_pk_mul_f32 v[64:65], v[48:49], v[56:57] op_sel_hi:[1,0]
	v_pk_mul_f32 v[62:63], v[62:63], v[70:71]
	v_pk_mul_f32 v[56:57], v[50:51], v[56:57] op_sel_hi:[1,0]
	v_exp_f32_e32 v64, v64
	v_exp_f32_e32 v65, v65
	v_pk_mul_f32 v[62:63], v[62:63], v[66:67]
	v_exp_f32_e32 v66, v56
	v_exp_f32_e32 v67, v57
	v_add_co_u32_e32 v76, vcc, s76, v132
	v_pk_mul_f32 v[48:49], v[48:49], v[52:53]
	s_nop 0
	v_addc_co_u32_e32 v77, vcc, 0, v133, vcc
	global_store_dwordx4 v[76:77], v[72:75], off
	v_cvt_pk_bf16_f32 v56, v60, v61
	v_pk_fma_f32 v[60:61], v[58:59], v[64:65], v[58:59] op_sel_hi:[0,1,0]
	v_pk_fma_f32 v[58:59], v[58:59], v[66:67], v[58:59] op_sel_hi:[0,1,0]
	v_rcp_f32_e32 v60, v60
	v_rcp_f32_e32 v61, v61
	v_rcp_f32_e32 v58, v58
	v_rcp_f32_e32 v59, v59
	v_pk_mul_f32 v[50:51], v[50:51], v[54:55]
	v_pk_mul_f32 v[48:49], v[48:49], v[60:61]
	v_cvt_pk_bf16_f32 v57, v62, v63
	v_pk_mul_f32 v[50:51], v[50:51], v[58:59]
	v_cvt_pk_bf16_f32 v58, v48, v49
	v_mul_f32_e32 v48, 0xbfb8aa3b, v137
	v_mul_f32_e32 v49, v137, v137
	v_pk_mul_f32 v[52:53], v[40:41], v[48:49] op_sel_hi:[1,0]
	v_pk_mul_f32 v[54:55], v[42:43], v[48:49] op_sel_hi:[1,0]
	v_cvt_pk_bf16_f32 v59, v50, v51
	v_rcp_f32_e32 v50, v49
	v_exp_f32_e32 v52, v52
	v_exp_f32_e32 v53, v53
	v_exp_f32_e32 v54, v54
	v_exp_f32_e32 v55, v55
	v_pk_mul_f32 v[40:41], v[40:41], v[44:45]
	v_pk_fma_f32 v[52:53], v[50:51], v[52:53], v[50:51] op_sel_hi:[0,1,0]
	v_rcp_f32_e32 v52, v52
	v_pk_fma_f32 v[54:55], v[50:51], v[54:55], v[50:51] op_sel_hi:[0,1,0]
	v_rcp_f32_e32 v53, v53
	v_rcp_f32_e32 v54, v54
	v_rcp_f32_e32 v55, v55
	v_pk_mul_f32 v[44:45], v[32:33], v[48:49] op_sel_hi:[1,0]
	v_pk_mul_f32 v[42:43], v[42:43], v[46:47]
	v_exp_f32_e32 v44, v44
	v_exp_f32_e32 v45, v45
	v_pk_mul_f32 v[46:47], v[34:35], v[48:49] op_sel_hi:[1,0]
	v_add_co_u32_e32 v60, vcc, s77, v132
	v_exp_f32_e32 v46, v46
	v_exp_f32_e32 v47, v47
	v_addc_co_u32_e32 v61, vcc, 0, v133, vcc
	v_pk_mul_f32 v[40:41], v[40:41], v[52:53]
	v_pk_mul_f32 v[42:43], v[42:43], v[54:55]
	global_store_dwordx4 v[60:61], v[56:59], off
	v_cvt_pk_bf16_f32 v40, v40, v41
	v_cvt_pk_bf16_f32 v41, v42, v43
	v_pk_fma_f32 v[42:43], v[50:51], v[44:45], v[50:51] op_sel_hi:[0,1,0]
	v_rcp_f32_e32 v42, v42
	v_rcp_f32_e32 v43, v43
	v_pk_fma_f32 v[44:45], v[50:51], v[46:47], v[50:51] op_sel_hi:[0,1,0]
	v_rcp_f32_e32 v44, v44
	v_rcp_f32_e32 v45, v45
	v_pk_mul_f32 v[32:33], v[32:33], v[36:37]
	v_pk_mul_f32 v[34:35], v[34:35], v[38:39]
	v_pk_mul_f32 v[32:33], v[32:33], v[42:43]
	v_pk_mul_f32 v[34:35], v[34:35], v[44:45]
	v_cvt_pk_bf16_f32 v42, v32, v33
	s_waitcnt lgkmcnt(0)
	v_mul_f32_e32 v32, 0xbfb8aa3b, v134
	v_mul_f32_e32 v33, v134, v134
	v_pk_mul_f32 v[36:37], v[24:25], v[32:33] op_sel_hi:[1,0]
	v_pk_mul_f32 v[38:39], v[26:27], v[32:33] op_sel_hi:[1,0]
	v_cvt_pk_bf16_f32 v43, v34, v35
	v_rcp_f32_e32 v34, v33
	v_exp_f32_e32 v36, v36
	v_exp_f32_e32 v37, v37
	v_exp_f32_e32 v38, v38
	v_exp_f32_e32 v39, v39
	v_pk_mul_f32 v[24:25], v[24:25], v[28:29]
	v_pk_fma_f32 v[36:37], v[34:35], v[36:37], v[34:35] op_sel_hi:[0,1,0]
	v_rcp_f32_e32 v36, v36
	v_pk_fma_f32 v[38:39], v[34:35], v[38:39], v[34:35] op_sel_hi:[0,1,0]
	v_rcp_f32_e32 v37, v37
	v_rcp_f32_e32 v38, v38
	v_rcp_f32_e32 v39, v39
	v_pk_mul_f32 v[28:29], v[16:17], v[32:33] op_sel_hi:[1,0]
	v_pk_mul_f32 v[26:27], v[26:27], v[30:31]
	v_exp_f32_e32 v28, v28
	v_exp_f32_e32 v29, v29
	v_pk_mul_f32 v[30:31], v[18:19], v[32:33] op_sel_hi:[1,0]
	v_add_co_u32_e32 v44, vcc, s80, v132
	v_exp_f32_e32 v30, v30
	v_exp_f32_e32 v31, v31
	v_addc_co_u32_e32 v45, vcc, 0, v133, vcc
	v_pk_mul_f32 v[24:25], v[24:25], v[36:37]
	v_pk_mul_f32 v[26:27], v[26:27], v[38:39]
	global_store_dwordx4 v[44:45], v[40:43], off
	v_cvt_pk_bf16_f32 v24, v24, v25
	v_cvt_pk_bf16_f32 v25, v26, v27
	v_pk_fma_f32 v[26:27], v[34:35], v[28:29], v[34:35] op_sel_hi:[0,1,0]
	v_rcp_f32_e32 v26, v26
	v_rcp_f32_e32 v27, v27
	v_pk_fma_f32 v[28:29], v[34:35], v[30:31], v[34:35] op_sel_hi:[0,1,0]
	v_rcp_f32_e32 v28, v28
	v_rcp_f32_e32 v29, v29
	v_pk_mul_f32 v[16:17], v[16:17], v[20:21]
	v_pk_mul_f32 v[18:19], v[18:19], v[22:23]
	v_pk_mul_f32 v[16:17], v[16:17], v[26:27]
	v_pk_mul_f32 v[18:19], v[18:19], v[28:29]
	v_cvt_pk_bf16_f32 v26, v16, v17
	v_mul_f32_e32 v16, 0xbfb8aa3b, v135
	v_mul_f32_e32 v17, v135, v135
	v_pk_mul_f32 v[20:21], v[8:9], v[16:17] op_sel_hi:[1,0]
	v_pk_mul_f32 v[22:23], v[10:11], v[16:17] op_sel_hi:[1,0]
	v_cvt_pk_bf16_f32 v27, v18, v19
	v_rcp_f32_e32 v18, v17
	v_exp_f32_e32 v20, v20
	v_exp_f32_e32 v21, v21
	v_exp_f32_e32 v22, v22
	v_exp_f32_e32 v23, v23
	v_pk_mul_f32 v[8:9], v[8:9], v[12:13]
	v_pk_fma_f32 v[20:21], v[18:19], v[20:21], v[18:19] op_sel_hi:[0,1,0]
	v_rcp_f32_e32 v20, v20
	v_pk_fma_f32 v[22:23], v[18:19], v[22:23], v[18:19] op_sel_hi:[0,1,0]
	v_rcp_f32_e32 v21, v21
	v_rcp_f32_e32 v22, v22
	v_rcp_f32_e32 v23, v23
	v_pk_mul_f32 v[12:13], v[0:1], v[16:17] op_sel_hi:[1,0]
	v_add_co_u32_e32 v28, vcc, s81, v132
	v_exp_f32_e32 v12, v12
	v_exp_f32_e32 v13, v13
	v_pk_mul_f32 v[10:11], v[10:11], v[14:15]
	v_addc_co_u32_e32 v29, vcc, 0, v133, vcc
	v_pk_mul_f32 v[8:9], v[8:9], v[20:21]
	v_pk_mul_f32 v[10:11], v[10:11], v[22:23]
	v_pk_mul_f32 v[14:15], v[2:3], v[16:17] op_sel_hi:[1,0]
	global_store_dwordx4 v[28:29], v[24:27], off
	v_exp_f32_e32 v14, v14
	v_exp_f32_e32 v15, v15
	v_cvt_pk_bf16_f32 v8, v8, v9
	v_cvt_pk_bf16_f32 v9, v10, v11
	v_pk_fma_f32 v[10:11], v[18:19], v[12:13], v[18:19] op_sel_hi:[0,1,0]
	v_rcp_f32_e32 v10, v10
	v_rcp_f32_e32 v11, v11
	v_pk_fma_f32 v[12:13], v[18:19], v[14:15], v[18:19] op_sel_hi:[0,1,0]
	v_pk_mul_f32 v[0:1], v[0:1], v[4:5]
	v_rcp_f32_e32 v12, v12
	v_rcp_f32_e32 v13, v13
	v_pk_mul_f32 v[0:1], v[0:1], v[10:11]
	v_pk_mul_f32 v[2:3], v[2:3], v[6:7]
	v_cvt_pk_bf16_f32 v10, v0, v1
	v_add_co_u32_e32 v0, vcc, 0xf2000, v132
	v_pk_mul_f32 v[2:3], v[2:3], v[12:13]
	s_nop 0
	v_addc_co_u32_e32 v1, vcc, 0, v133, vcc
	s_andn2_b64 vcc, exec, s[6:7]
	s_mov_b64 s[6:7], -1
	v_cvt_pk_bf16_f32 v11, v2, v3
	global_store_dwordx4 v[0:1], v[8:11], off
	s_cbranch_vccnz .LBB0_520
	s_andn2_b64 vcc, exec, s[12:13]
	s_cbranch_vccnz .LBB0_519
	s_barrier
	s_branch .LBB0_519

.LBB0_1257:
	s_cmp_eq_u32 s22, s33
	s_cselect_b32 s13, 0, 0x400
	v_add_u32_e32 v132, s13, v146
	ds_read2_b32 v[152:153], v132 offset1:16
	ds_read2_b32 v[138:139], v132 offset0:32 offset1:48
	ds_read2_b32 v[136:137], v132 offset0:128 offset1:144
	ds_read2_b32 v[134:135], v132 offset0:160 offset1:176
	v_lshl_add_u32 v133, s22, 8, v144
	v_mov_b64_e32 v[154:155], s[66:67]
	s_waitcnt lgkmcnt(3)
	v_mul_f32_e32 v156, 0xbfb8aa3b, v152
	v_mad_i64_i32 v[154:155], s[24:25], v133, s68, v[154:155]
	v_mul_f32_e32 v133, v152, v152
	v_pk_mul_f32 v[158:159], v[120:121], v[156:157] op_sel_hi:[1,0]
	v_pk_mul_f32 v[160:161], v[122:123], v[156:157] op_sel_hi:[1,0]
	v_rcp_f32_e32 v152, v133
	v_exp_f32_e32 v158, v158
	v_exp_f32_e32 v159, v159
	v_exp_f32_e32 v160, v160
	v_exp_f32_e32 v161, v161
	s_lshl_b32 s13, s74, 7
	v_subrev_u32_e32 v132, s13, v145
	v_ashrrev_i32_e32 v133, 31, v132
	v_lshl_add_u64 v[132:133], v[132:133], 1, v[154:155]
	v_pk_fma_f32 v[154:155], v[152:153], v[158:159], v[152:153] op_sel_hi:[0,1,0]
	v_pk_fma_f32 v[158:159], v[152:153], v[160:161], v[152:153] op_sel_hi:[0,1,0]
	v_rcp_f32_e32 v154, v154
	v_rcp_f32_e32 v155, v155
	v_rcp_f32_e32 v158, v158
	v_rcp_f32_e32 v159, v159
	v_pk_mul_f32 v[120:121], v[120:121], v[124:125]
	v_pk_mul_f32 v[124:125], v[112:113], v[156:157] op_sel_hi:[1,0]
	v_pk_mul_f32 v[122:123], v[122:123], v[126:127]
	v_exp_f32_e32 v124, v124
	v_exp_f32_e32 v125, v125
	v_pk_mul_f32 v[126:127], v[114:115], v[156:157] op_sel_hi:[1,0]
	v_pk_mul_f32 v[120:121], v[120:121], v[154:155]
	v_exp_f32_e32 v126, v126
	v_exp_f32_e32 v127, v127
	v_pk_mul_f32 v[122:123], v[122:123], v[158:159]
	v_cvt_pk_bf16_f32 v120, v120, v121
	v_pk_mul_f32 v[112:113], v[112:113], v[116:117]
	v_cvt_pk_bf16_f32 v121, v122, v123
	v_pk_fma_f32 v[122:123], v[152:153], v[124:125], v[152:153] op_sel_hi:[0,1,0]
	v_rcp_f32_e32 v122, v122
	v_rcp_f32_e32 v123, v123
	v_pk_fma_f32 v[124:125], v[152:153], v[126:127], v[152:153] op_sel_hi:[0,1,0]
	v_rcp_f32_e32 v124, v124
	v_rcp_f32_e32 v125, v125
	v_pk_mul_f32 v[112:113], v[112:113], v[122:123]
	v_pk_mul_f32 v[114:115], v[114:115], v[118:119]
	v_cvt_pk_bf16_f32 v122, v112, v113
	v_mul_f32_e32 v112, 0xbfb8aa3b, v153
	v_mul_f32_e32 v113, v153, v153
	v_pk_mul_f32 v[114:115], v[114:115], v[124:125]
	v_pk_mul_f32 v[118:119], v[104:105], v[112:113] op_sel_hi:[1,0]
	v_pk_mul_f32 v[124:125], v[106:107], v[112:113] op_sel_hi:[1,0]
	v_rcp_f32_e32 v116, v113
	v_exp_f32_e32 v118, v118
	v_exp_f32_e32 v119, v119
	v_exp_f32_e32 v124, v124
	v_exp_f32_e32 v125, v125
	v_cvt_pk_bf16_f32 v123, v114, v115
	v_pk_fma_f32 v[114:115], v[116:117], v[118:119], v[116:117] op_sel_hi:[0,1,0]
	v_rcp_f32_e32 v114, v114
	v_pk_fma_f32 v[118:119], v[116:117], v[124:125], v[116:117] op_sel_hi:[0,1,0]
	v_rcp_f32_e32 v115, v115
	v_rcp_f32_e32 v118, v118
	v_rcp_f32_e32 v119, v119
	v_pk_mul_f32 v[104:105], v[104:105], v[108:109]
	v_pk_mul_f32 v[108:109], v[96:97], v[112:113] op_sel_hi:[1,0]
	v_pk_mul_f32 v[106:107], v[106:107], v[110:111]
	v_exp_f32_e32 v108, v108
	v_exp_f32_e32 v109, v109
	v_pk_mul_f32 v[110:111], v[98:99], v[112:113] op_sel_hi:[1,0]
	v_pk_mul_f32 v[104:105], v[104:105], v[114:115]
	v_exp_f32_e32 v110, v110
	v_exp_f32_e32 v111, v111
	v_pk_mul_f32 v[106:107], v[106:107], v[118:119]
	global_store_dwordx4 v[132:133], v[120:123], off
	v_cvt_pk_bf16_f32 v104, v104, v105
	v_cvt_pk_bf16_f32 v105, v106, v107
	v_pk_fma_f32 v[106:107], v[116:117], v[108:109], v[116:117] op_sel_hi:[0,1,0]
	v_rcp_f32_e32 v106, v106
	v_rcp_f32_e32 v107, v107
	v_pk_fma_f32 v[108:109], v[116:117], v[110:111], v[116:117] op_sel_hi:[0,1,0]
	v_rcp_f32_e32 v108, v108
	v_rcp_f32_e32 v109, v109
	v_pk_mul_f32 v[96:97], v[96:97], v[100:101]
	v_pk_mul_f32 v[98:99], v[98:99], v[102:103]
	v_pk_mul_f32 v[96:97], v[96:97], v[106:107]
	v_pk_mul_f32 v[98:99], v[98:99], v[108:109]
	v_cvt_pk_bf16_f32 v106, v96, v97
	s_waitcnt lgkmcnt(2)
	v_mul_f32_e32 v96, 0xbfb8aa3b, v138
	v_mul_f32_e32 v97, v138, v138
	v_pk_mul_f32 v[100:101], v[88:89], v[96:97] op_sel_hi:[1,0]
	v_pk_mul_f32 v[102:103], v[90:91], v[96:97] op_sel_hi:[1,0]
	v_cvt_pk_bf16_f32 v107, v98, v99
	v_rcp_f32_e32 v98, v97
	v_exp_f32_e32 v100, v100
	v_exp_f32_e32 v101, v101
	v_exp_f32_e32 v102, v102
	v_exp_f32_e32 v103, v103
	v_pk_mul_f32 v[88:89], v[88:89], v[92:93]
	v_pk_fma_f32 v[100:101], v[98:99], v[100:101], v[98:99] op_sel_hi:[0,1,0]
	v_rcp_f32_e32 v100, v100
	v_pk_fma_f32 v[102:103], v[98:99], v[102:103], v[98:99] op_sel_hi:[0,1,0]
	v_rcp_f32_e32 v101, v101
	v_rcp_f32_e32 v102, v102
	v_rcp_f32_e32 v103, v103
	v_pk_mul_f32 v[92:93], v[80:81], v[96:97] op_sel_hi:[1,0]
	v_pk_mul_f32 v[90:91], v[90:91], v[94:95]
	v_exp_f32_e32 v92, v92
	v_exp_f32_e32 v93, v93
	v_pk_mul_f32 v[94:95], v[82:83], v[96:97] op_sel_hi:[1,0]
	v_add_co_u32_e32 v108, vcc, s55, v132
	v_exp_f32_e32 v94, v94
	v_exp_f32_e32 v95, v95
	v_addc_co_u32_e32 v109, vcc, 0, v133, vcc
	v_pk_mul_f32 v[88:89], v[88:89], v[100:101]
	v_pk_mul_f32 v[90:91], v[90:91], v[102:103]
	global_store_dwordx4 v[108:109], v[104:107], off
	s_and_b64 vcc, exec, s[10:11]
	s_cbranch_vccz .Lepibar_p6
	s_barrier
.Lepibar_p6:
	v_cvt_pk_bf16_f32 v88, v88, v89
	v_cvt_pk_bf16_f32 v89, v90, v91
	v_pk_fma_f32 v[90:91], v[98:99], v[92:93], v[98:99] op_sel_hi:[0,1,0]
	v_rcp_f32_e32 v90, v90
	v_rcp_f32_e32 v91, v91
	v_pk_fma_f32 v[92:93], v[98:99], v[94:95], v[98:99] op_sel_hi:[0,1,0]
	v_rcp_f32_e32 v92, v92
	v_rcp_f32_e32 v93, v93
	v_pk_mul_f32 v[80:81], v[80:81], v[84:85]
	v_pk_mul_f32 v[82:83], v[82:83], v[86:87]
	v_pk_mul_f32 v[80:81], v[80:81], v[90:91]
	v_pk_mul_f32 v[82:83], v[82:83], v[92:93]
	v_cvt_pk_bf16_f32 v90, v80, v81
	v_mul_f32_e32 v80, 0xbfb8aa3b, v139
	v_mul_f32_e32 v81, v139, v139
	v_pk_mul_f32 v[84:85], v[72:73], v[80:81] op_sel_hi:[1,0]
	v_pk_mul_f32 v[86:87], v[74:75], v[80:81] op_sel_hi:[1,0]
	v_cvt_pk_bf16_f32 v91, v82, v83
	v_rcp_f32_e32 v82, v81
	v_exp_f32_e32 v84, v84
	v_exp_f32_e32 v85, v85
	v_exp_f32_e32 v86, v86
	v_exp_f32_e32 v87, v87
	v_pk_mul_f32 v[72:73], v[72:73], v[76:77]
	v_pk_fma_f32 v[84:85], v[82:83], v[84:85], v[82:83] op_sel_hi:[0,1,0]
	v_rcp_f32_e32 v84, v84
	v_pk_fma_f32 v[86:87], v[82:83], v[86:87], v[82:83] op_sel_hi:[0,1,0]
	v_rcp_f32_e32 v85, v85
	v_rcp_f32_e32 v86, v86
	v_rcp_f32_e32 v87, v87
	v_pk_mul_f32 v[76:77], v[56:57], v[80:81] op_sel_hi:[1,0]
	v_pk_mul_f32 v[74:75], v[74:75], v[78:79]
	v_exp_f32_e32 v76, v76
	v_exp_f32_e32 v77, v77
	v_pk_mul_f32 v[78:79], v[58:59], v[80:81] op_sel_hi:[1,0]
	v_add_co_u32_e32 v92, vcc, s69, v132
	v_exp_f32_e32 v78, v78
	v_exp_f32_e32 v79, v79
	v_addc_co_u32_e32 v93, vcc, 0, v133, vcc
	v_pk_mul_f32 v[72:73], v[72:73], v[84:85]
	v_pk_mul_f32 v[74:75], v[74:75], v[86:87]
	global_store_dwordx4 v[92:93], v[88:91], off
	v_cvt_pk_bf16_f32 v72, v72, v73
	v_cvt_pk_bf16_f32 v73, v74, v75
	v_pk_fma_f32 v[74:75], v[82:83], v[76:77], v[82:83] op_sel_hi:[0,1,0]
	v_rcp_f32_e32 v74, v74
	v_rcp_f32_e32 v75, v75
	v_pk_fma_f32 v[76:77], v[82:83], v[78:79], v[82:83] op_sel_hi:[0,1,0]
	v_rcp_f32_e32 v76, v76
	v_rcp_f32_e32 v77, v77
	v_pk_mul_f32 v[56:57], v[56:57], v[64:65]
	v_pk_mul_f32 v[58:59], v[58:59], v[66:67]
	v_pk_mul_f32 v[56:57], v[56:57], v[74:75]
	v_pk_mul_f32 v[58:59], v[58:59], v[76:77]
	v_cvt_pk_bf16_f32 v74, v56, v57
	s_waitcnt lgkmcnt(1)
	v_mul_f32_e32 v56, 0xbfb8aa3b, v136
	v_mul_f32_e32 v57, v136, v136
	v_pk_mul_f32 v[64:65], v[60:61], v[56:57] op_sel_hi:[1,0]
	v_cvt_pk_bf16_f32 v75, v58, v59
	v_rcp_f32_e32 v58, v57
	v_exp_f32_e32 v64, v64
	v_exp_f32_e32 v65, v65
	v_pk_mul_f32 v[66:67], v[62:63], v[56:57] op_sel_hi:[1,0]
	v_pk_mul_f32 v[60:61], v[60:61], v[68:69]
	v_exp_f32_e32 v66, v66
	v_exp_f32_e32 v67, v67
	v_pk_fma_f32 v[64:65], v[58:59], v[64:65], v[58:59] op_sel_hi:[0,1,0]
	v_rcp_f32_e32 v64, v64
	v_rcp_f32_e32 v65, v65
	v_pk_fma_f32 v[66:67], v[58:59], v[66:67], v[58:59] op_sel_hi:[0,1,0]
	v_rcp_f32_e32 v66, v66
	v_rcp_f32_e32 v67, v67
	v_pk_mul_f32 v[60:61], v[60:61], v[64:65]
	v_pk_mul_f32 v[64:65], v[48:49], v[56:57] op_sel_hi:[1,0]
	v_pk_mul_f32 v[62:63], v[62:63], v[70:71]
	v_pk_mul_f32 v[56:57], v[50:51], v[56:57] op_sel_hi:[1,0]
	v_exp_f32_e32 v64, v64
	v_exp_f32_e32 v65, v65
	v_pk_mul_f32 v[62:63], v[62:63], v[66:67]
	v_exp_f32_e32 v66, v56
	v_exp_f32_e32 v67, v57
	v_add_co_u32_e32 v76, vcc, s70, v132
	v_pk_mul_f32 v[48:49], v[48:49], v[52:53]
	s_nop 0
	v_addc_co_u32_e32 v77, vcc, 0, v133, vcc
	global_store_dwordx4 v[76:77], v[72:75], off
	v_cvt_pk_bf16_f32 v56, v60, v61
	v_pk_fma_f32 v[60:61], v[58:59], v[64:65], v[58:59] op_sel_hi:[0,1,0]
	v_pk_fma_f32 v[58:59], v[58:59], v[66:67], v[58:59] op_sel_hi:[0,1,0]
	v_rcp_f32_e32 v60, v60
	v_rcp_f32_e32 v61, v61
	v_rcp_f32_e32 v58, v58
	v_rcp_f32_e32 v59, v59
	v_pk_mul_f32 v[50:51], v[50:51], v[54:55]
	v_pk_mul_f32 v[48:49], v[48:49], v[60:61]
	v_cvt_pk_bf16_f32 v57, v62, v63
	v_pk_mul_f32 v[50:51], v[50:51], v[58:59]
	v_cvt_pk_bf16_f32 v58, v48, v49
	v_mul_f32_e32 v48, 0xbfb8aa3b, v137
	v_mul_f32_e32 v49, v137, v137
	v_pk_mul_f32 v[52:53], v[40:41], v[48:49] op_sel_hi:[1,0]
	v_pk_mul_f32 v[54:55], v[42:43], v[48:49] op_sel_hi:[1,0]
	v_cvt_pk_bf16_f32 v59, v50, v51
	v_rcp_f32_e32 v50, v49
	v_exp_f32_e32 v52, v52
	v_exp_f32_e32 v53, v53
	v_exp_f32_e32 v54, v54
	v_exp_f32_e32 v55, v55
	v_pk_mul_f32 v[40:41], v[40:41], v[44:45]
	v_pk_fma_f32 v[52:53], v[50:51], v[52:53], v[50:51] op_sel_hi:[0,1,0]
	v_rcp_f32_e32 v52, v52
	v_pk_fma_f32 v[54:55], v[50:51], v[54:55], v[50:51] op_sel_hi:[0,1,0]
	v_rcp_f32_e32 v53, v53
	v_rcp_f32_e32 v54, v54
	v_rcp_f32_e32 v55, v55
	v_pk_mul_f32 v[44:45], v[32:33], v[48:49] op_sel_hi:[1,0]
	v_pk_mul_f32 v[42:43], v[42:43], v[46:47]
	v_exp_f32_e32 v44, v44
	v_exp_f32_e32 v45, v45
	v_pk_mul_f32 v[46:47], v[34:35], v[48:49] op_sel_hi:[1,0]
	v_add_co_u32_e32 v60, vcc, s71, v132
	v_exp_f32_e32 v46, v46
	v_exp_f32_e32 v47, v47
	v_addc_co_u32_e32 v61, vcc, 0, v133, vcc
	v_pk_mul_f32 v[40:41], v[40:41], v[52:53]
	v_pk_mul_f32 v[42:43], v[42:43], v[54:55]
	global_store_dwordx4 v[60:61], v[56:59], off
	v_cvt_pk_bf16_f32 v40, v40, v41
	v_cvt_pk_bf16_f32 v41, v42, v43
	v_pk_fma_f32 v[42:43], v[50:51], v[44:45], v[50:51] op_sel_hi:[0,1,0]
	v_rcp_f32_e32 v42, v42
	v_rcp_f32_e32 v43, v43
	v_pk_fma_f32 v[44:45], v[50:51], v[46:47], v[50:51] op_sel_hi:[0,1,0]
	v_rcp_f32_e32 v44, v44
	v_rcp_f32_e32 v45, v45
	v_pk_mul_f32 v[32:33], v[32:33], v[36:37]
	v_pk_mul_f32 v[34:35], v[34:35], v[38:39]
	v_pk_mul_f32 v[32:33], v[32:33], v[42:43]
	v_pk_mul_f32 v[34:35], v[34:35], v[44:45]
	v_cvt_pk_bf16_f32 v42, v32, v33
	s_waitcnt lgkmcnt(0)
	v_mul_f32_e32 v32, 0xbfb8aa3b, v134
	v_mul_f32_e32 v33, v134, v134
	v_pk_mul_f32 v[36:37], v[24:25], v[32:33] op_sel_hi:[1,0]
	v_pk_mul_f32 v[38:39], v[26:27], v[32:33] op_sel_hi:[1,0]
	v_cvt_pk_bf16_f32 v43, v34, v35
	v_rcp_f32_e32 v34, v33
	v_exp_f32_e32 v36, v36
	v_exp_f32_e32 v37, v37
	v_exp_f32_e32 v38, v38
	v_exp_f32_e32 v39, v39
	v_pk_mul_f32 v[24:25], v[24:25], v[28:29]
	v_pk_fma_f32 v[36:37], v[34:35], v[36:37], v[34:35] op_sel_hi:[0,1,0]
	v_rcp_f32_e32 v36, v36
	v_pk_fma_f32 v[38:39], v[34:35], v[38:39], v[34:35] op_sel_hi:[0,1,0]
	v_rcp_f32_e32 v37, v37
	v_rcp_f32_e32 v38, v38
	v_rcp_f32_e32 v39, v39
	v_pk_mul_f32 v[28:29], v[16:17], v[32:33] op_sel_hi:[1,0]
	v_pk_mul_f32 v[26:27], v[26:27], v[30:31]
	v_exp_f32_e32 v28, v28
	v_exp_f32_e32 v29, v29
	v_pk_mul_f32 v[30:31], v[18:19], v[32:33] op_sel_hi:[1,0]
	v_add_co_u32_e32 v44, vcc, s72, v132
	v_exp_f32_e32 v30, v30
	v_exp_f32_e32 v31, v31
	v_addc_co_u32_e32 v45, vcc, 0, v133, vcc
	v_pk_mul_f32 v[24:25], v[24:25], v[36:37]
	v_pk_mul_f32 v[26:27], v[26:27], v[38:39]
	global_store_dwordx4 v[44:45], v[40:43], off
	v_cvt_pk_bf16_f32 v24, v24, v25
	v_cvt_pk_bf16_f32 v25, v26, v27
	v_pk_fma_f32 v[26:27], v[34:35], v[28:29], v[34:35] op_sel_hi:[0,1,0]
	v_rcp_f32_e32 v26, v26
	v_rcp_f32_e32 v27, v27
	v_pk_fma_f32 v[28:29], v[34:35], v[30:31], v[34:35] op_sel_hi:[0,1,0]
	v_rcp_f32_e32 v28, v28
	v_rcp_f32_e32 v29, v29
	v_pk_mul_f32 v[16:17], v[16:17], v[20:21]
	v_pk_mul_f32 v[18:19], v[18:19], v[22:23]
	v_pk_mul_f32 v[16:17], v[16:17], v[26:27]
	v_pk_mul_f32 v[18:19], v[18:19], v[28:29]
	v_cvt_pk_bf16_f32 v26, v16, v17
	v_mul_f32_e32 v16, 0xbfb8aa3b, v135
	v_mul_f32_e32 v17, v135, v135
	v_pk_mul_f32 v[20:21], v[8:9], v[16:17] op_sel_hi:[1,0]
	v_pk_mul_f32 v[22:23], v[10:11], v[16:17] op_sel_hi:[1,0]
	v_cvt_pk_bf16_f32 v27, v18, v19
	v_rcp_f32_e32 v18, v17
	v_exp_f32_e32 v20, v20
	v_exp_f32_e32 v21, v21
	v_exp_f32_e32 v22, v22
	v_exp_f32_e32 v23, v23
	v_pk_mul_f32 v[8:9], v[8:9], v[12:13]
	v_pk_fma_f32 v[20:21], v[18:19], v[20:21], v[18:19] op_sel_hi:[0,1,0]
	v_rcp_f32_e32 v20, v20
	v_pk_fma_f32 v[22:23], v[18:19], v[22:23], v[18:19] op_sel_hi:[0,1,0]
	v_rcp_f32_e32 v21, v21
	v_rcp_f32_e32 v22, v22
	v_rcp_f32_e32 v23, v23
	v_pk_mul_f32 v[12:13], v[0:1], v[16:17] op_sel_hi:[1,0]
	v_add_co_u32_e32 v28, vcc, s73, v132
	v_exp_f32_e32 v12, v12
	v_exp_f32_e32 v13, v13
	v_pk_mul_f32 v[10:11], v[10:11], v[14:15]
	v_addc_co_u32_e32 v29, vcc, 0, v133, vcc
	v_pk_mul_f32 v[8:9], v[8:9], v[20:21]
	v_pk_mul_f32 v[10:11], v[10:11], v[22:23]
	v_pk_mul_f32 v[14:15], v[2:3], v[16:17] op_sel_hi:[1,0]
	global_store_dwordx4 v[28:29], v[24:27], off
	v_exp_f32_e32 v14, v14
	v_exp_f32_e32 v15, v15
	v_cvt_pk_bf16_f32 v8, v8, v9
	v_cvt_pk_bf16_f32 v9, v10, v11
	v_pk_fma_f32 v[10:11], v[18:19], v[12:13], v[18:19] op_sel_hi:[0,1,0]
	v_rcp_f32_e32 v10, v10
	v_rcp_f32_e32 v11, v11
	v_pk_fma_f32 v[12:13], v[18:19], v[14:15], v[18:19] op_sel_hi:[0,1,0]
	v_pk_mul_f32 v[0:1], v[0:1], v[4:5]
	v_rcp_f32_e32 v12, v12
	v_rcp_f32_e32 v13, v13
	v_pk_mul_f32 v[0:1], v[0:1], v[10:11]
	v_pk_mul_f32 v[2:3], v[2:3], v[6:7]
	v_cvt_pk_bf16_f32 v10, v0, v1
	v_add_co_u32_e32 v0, vcc, 0xf2000, v132
	v_pk_mul_f32 v[2:3], v[2:3], v[12:13]
	s_nop 0
	v_addc_co_u32_e32 v1, vcc, 0, v133, vcc
	s_andn2_b64 vcc, exec, s[0:1]
	s_mov_b64 s[0:1], -1
	v_cvt_pk_bf16_f32 v11, v2, v3
	global_store_dwordx4 v[0:1], v[8:11], off
	s_cbranch_vccnz .LBB0_1250
	s_andn2_b64 vcc, exec, s[6:7]
	s_cbranch_vccnz .LBB0_1249
	s_barrier
	s_branch .LBB0_1249
